# v56 plus SwiGLU epilogue H stores transposed through wave-private LDS so adjacent lanes write adjacent 16-byte chunks of a row
# baseline (speedup 1.0000x reference)
; __device__ __forceinline__ unsigned cvt_pk_bf16(float lo, float hi) { f32x2 v = {lo, hi}; bf16x2_t b = __builtin_convertvector(v, bf16x2_t); return __builtin_bit_cast(unsigned, b); }
; __device__ __forceinline__ float silu_mul(float g, float u) { return g * u * __builtin_amdgcn_rcpf(1.0f + __builtin_amdgcn_exp2f(-1.4426950408889634f * g)); }
;     __device__ __forceinline__ void operator()(const f32x4 (&acc)[2][2][4][2], const Unit& u, int wr, int wc, int fr, int fq) const {
;     ...
;             for (int m = 0; m < 4; ++m) { const int row = row0 + ai * HALF + m * 16; bf16_t* rowp = O + (size_t)row * ldc + col0;
;                 float r = 1.0f; if (rowscale) r = __builtin_amdgcn_rsqf(rs[row] * rs_invn + 1e-6f);
;                 if (mode == 2) {
;                     const f32x4 g0 = acc[ai][0][m][0] * r, g1 = acc[ai][0][m][1] * r, u0 = acc[ai][1][m][0] * r, u1 = acc[ai][1][m][1] * r;
;                     u32x4 w; w.x = cvt_pk_bf16(silu_mul(g0[0], u0[0]), silu_mul(g0[1], u0[1])); w.y = cvt_pk_bf16(silu_mul(g0[2], u0[2]), silu_mul(g0[3], u0[3]));
;                     w.z = cvt_pk_bf16(silu_mul(g1[0], u1[0]), silu_mul(g1[1], u1[1])); w.w = cvt_pk_bf16(silu_mul(g1[2], u1[2]), silu_mul(g1[3], u1[3]));
;                     *(u32x4*)rowp = w;
.LBB0_94:
	v_and_b32_e32 v138, 15, v217
	v_lshrrev_b32_e32 v139, 4, v217
	v_lshrrev_b32_e32 v140, 2, v217
	v_and_b32_e32 v141, 3, v217
	v_and_b32_e32 v142, 3, v138
	v_xor_b32_e32 v142, v139, v142
	v_lshlrev_b32_e32 v142, 4, v142
	v_lshl_add_u32 v142, v138, 6, v142
	v_add_u32_e32 v248, s31, v142
	v_and_b32_e32 v142, 3, v140
	v_xor_b32_e32 v142, v141, v142
	v_lshlrev_b32_e32 v142, 4, v142
	v_lshl_add_u32 v142, v140, 6, v142
	v_add_u32_e32 v249, s31, v142
	s_lshl_b32 s78, s86, 1
	v_sub_u32_e32 v142, v140, v138
	v_sub_u32_e32 v143, v141, v139
	v_mul_i32_i24_e32 v250, s78, v142
	v_lshl_add_u32 v250, v143, 4, v250
	v_ashrrev_i32_e32 v251, 31, v250
	v_cndmask_b32_e64 v136, 0, 1, s[70:71]
	v_cmp_ne_u32_e64 s[44:45], 1, v136
	s_andn2_b64 vcc, exec, s[70:71]
	v_lshl_add_u64 v[136:137], v[156:157], 2, s[92:93]
	s_cbranch_vccnz .LBB0_96
	global_load_dword v240, v[136:137], off
	global_load_dword v241, v[136:137], off offset:64
	global_load_dword v242, v[136:137], off offset:128
	global_load_dword v243, v[136:137], off offset:192
	global_load_dword v244, v[136:137], off offset:512
	global_load_dword v245, v[136:137], off offset:576
	global_load_dword v246, v[136:137], off offset:640
	global_load_dword v247, v[136:137], off offset:704
	s_waitcnt vmcnt(0)
	v_fma_f32 v138, s9, v240, v214
	v_rsq_f32_e32 v162, v138
	s_branch .LBB0_97

; __device__ __forceinline__ unsigned cvt_pk_bf16(float lo, float hi) { f32x2 v = {lo, hi}; bf16x2_t b = __builtin_convertvector(v, bf16x2_t); return __builtin_bit_cast(unsigned, b); }
; __device__ __forceinline__ float silu_mul(float g, float u) { return g * u * __builtin_amdgcn_rcpf(1.0f + __builtin_amdgcn_exp2f(-1.4426950408889634f * g)); }
;     __device__ __forceinline__ void operator()(const f32x4 (&acc)[2][2][4][2], const Unit& u, int wr, int wc, int fr, int fq) const {
;     ...
;                 if (mode == 2) {
;                     const f32x4 g0 = acc[ai][0][m][0] * r, g1 = acc[ai][0][m][1] * r, u0 = acc[ai][1][m][0] * r, u1 = acc[ai][1][m][1] * r;
;                     u32x4 w; w.x = cvt_pk_bf16(silu_mul(g0[0], u0[0]), silu_mul(g0[1], u0[1])); w.y = cvt_pk_bf16(silu_mul(g0[2], u0[2]), silu_mul(g0[3], u0[3]));
;                     w.z = cvt_pk_bf16(silu_mul(g1[0], u1[0]), silu_mul(g1[1], u1[1])); w.w = cvt_pk_bf16(silu_mul(g1[2], u1[2]), silu_mul(g1[3], u1[3]));
;                     *(u32x4*)rowp = w;
.LBB0_110:
	v_mov_b32_e32 v166, v162
	s_waitcnt lgkmcnt(0)
	v_mov_b32_e32 v167, v162
	v_pk_mul_f32 v[168:169], v[126:127], v[166:167]
	v_pk_mul_f32 v[170:171], v[124:125], v[162:163]
	v_pk_mul_f32 v[172:173], v[120:121], v[162:163]
	v_mul_f32_e32 v162, 0xbfb8aa3b, v164
	v_mul_f32_e32 v163, 0xbfb8aa3b, v165
	v_pk_mul_f32 v[168:169], v[160:161], v[168:169]
	v_mul_f32_e32 v160, 0xbfb8aa3b, v160
	v_mul_f32_e32 v161, 0xbfb8aa3b, v161
	v_exp_f32_e32 v162, v162
	v_exp_f32_e32 v163, v163
	v_exp_f32_e32 v160, v160
	v_exp_f32_e32 v161, v161
	v_add_f32_e32 v162, 1.0, v162
	v_add_f32_e32 v163, 1.0, v163
	v_add_f32_e32 v160, 1.0, v160
	v_add_f32_e32 v161, 1.0, v161
	v_rcp_f32_e32 v162, v162
	v_rcp_f32_e32 v163, v163
	v_rcp_f32_e32 v160, v160
	v_rcp_f32_e32 v161, v161
	v_pk_mul_f32 v[164:165], v[164:165], v[170:171]
	v_pk_mul_f32 v[166:167], v[122:123], v[166:167]
	v_pk_mul_f32 v[162:163], v[164:165], v[162:163]
	v_pk_mul_f32 v[160:161], v[168:169], v[160:161]
	v_cvt_pk_bf16_f32 v162, v162, v163
	v_cvt_pk_bf16_f32 v163, v160, v161
	v_mul_f32_e32 v160, 0xbfb8aa3b, v158
	v_mul_f32_e32 v161, 0xbfb8aa3b, v159
	v_pk_mul_f32 v[166:167], v[142:143], v[166:167]
	v_mul_f32_e32 v142, 0xbfb8aa3b, v142
	v_mul_f32_e32 v143, 0xbfb8aa3b, v143
	v_exp_f32_e32 v160, v160
	v_exp_f32_e32 v161, v161
	v_exp_f32_e32 v142, v142
	v_exp_f32_e32 v143, v143
	v_add_f32_e32 v160, 1.0, v160
	v_add_f32_e32 v161, 1.0, v161
	v_add_f32_e32 v142, 1.0, v142
	v_add_f32_e32 v143, 1.0, v143
	v_rcp_f32_e32 v160, v160
	v_rcp_f32_e32 v161, v161
	v_rcp_f32_e32 v142, v142
	v_rcp_f32_e32 v143, v143
	v_pk_mul_f32 v[158:159], v[158:159], v[172:173]
	v_pk_mul_f32 v[142:143], v[166:167], v[142:143]
	v_pk_mul_f32 v[158:159], v[158:159], v[160:161]
	v_cvt_pk_bf16_f32 v165, v142, v143
	v_cvt_pk_bf16_f32 v164, v158, v159
	ds_write_b128 v248, v[162:165] offset:49152
	s_waitcnt lgkmcnt(0)
	ds_read_b128 v[162:165], v249 offset:49152
	v_lshl_add_u64 v[140:141], v[140:141], 0, v[250:251]
	s_waitcnt lgkmcnt(0)
	global_store_dwordx4 v[140:141], v[162:165], off
	s_and_b64 vcc, exec, s[44:45]
	s_cbranch_vccz .LBB0_100

; __device__ __forceinline__ unsigned cvt_pk_bf16(float lo, float hi) { f32x2 v = {lo, hi}; bf16x2_t b = __builtin_convertvector(v, bf16x2_t); return __builtin_bit_cast(unsigned, b); }
; __device__ __forceinline__ float silu_mul(float g, float u) { return g * u * __builtin_amdgcn_rcpf(1.0f + __builtin_amdgcn_exp2f(-1.4426950408889634f * g)); }
;     __device__ __forceinline__ void operator()(const f32x4 (&acc)[2][2][4][2], const Unit& u, int wr, int wc, int fr, int fq) const {
;     ...
;                 if (mode == 2) {
;                     const f32x4 g0 = acc[ai][0][m][0] * r, g1 = acc[ai][0][m][1] * r, u0 = acc[ai][1][m][0] * r, u1 = acc[ai][1][m][1] * r;
;                     u32x4 w; w.x = cvt_pk_bf16(silu_mul(g0[0], u0[0]), silu_mul(g0[1], u0[1])); w.y = cvt_pk_bf16(silu_mul(g0[2], u0[2]), silu_mul(g0[3], u0[3]));
;                     w.z = cvt_pk_bf16(silu_mul(g1[0], u1[0]), silu_mul(g1[1], u1[1])); w.w = cvt_pk_bf16(silu_mul(g1[2], u1[2]), silu_mul(g1[3], u1[3]));
;                     *(u32x4*)rowp = w;
.LBB0_125:
	v_mov_b32_e32 v166, v164
	s_waitcnt lgkmcnt(0)
	v_mov_b32_e32 v167, v164
	v_pk_mul_f32 v[168:169], v[104:105], v[166:167]
	v_mul_f32_e32 v172, 0xbfb8aa3b, v162
	v_mul_f32_e32 v173, 0xbfb8aa3b, v163
	v_pk_mul_f32 v[168:169], v[160:161], v[168:169]
	v_mul_f32_e32 v160, 0xbfb8aa3b, v160
	v_mul_f32_e32 v161, 0xbfb8aa3b, v161
	v_exp_f32_e32 v172, v172
	v_exp_f32_e32 v173, v173
	v_exp_f32_e32 v160, v160
	v_exp_f32_e32 v161, v161
	v_add_f32_e32 v172, 1.0, v172
	v_add_f32_e32 v173, 1.0, v173
	v_add_f32_e32 v160, 1.0, v160
	v_add_f32_e32 v161, 1.0, v161
	v_rcp_f32_e32 v172, v172
	v_rcp_f32_e32 v173, v173
	v_rcp_f32_e32 v160, v160
	v_rcp_f32_e32 v161, v161
	v_pk_mul_f32 v[170:171], v[102:103], v[164:165]
	v_pk_mul_f32 v[166:167], v[100:101], v[166:167]
	v_pk_mul_f32 v[162:163], v[162:163], v[170:171]
	v_pk_mul_f32 v[160:161], v[168:169], v[160:161]
	v_pk_mul_f32 v[162:163], v[162:163], v[172:173]
	v_pk_mul_f32 v[166:167], v[142:143], v[166:167]
	v_cvt_pk_bf16_f32 v162, v162, v163
	v_cvt_pk_bf16_f32 v163, v160, v161
	v_mul_f32_e32 v160, 0xbfb8aa3b, v158
	v_mul_f32_e32 v161, 0xbfb8aa3b, v159
	v_mul_f32_e32 v142, 0xbfb8aa3b, v142
	v_mul_f32_e32 v143, 0xbfb8aa3b, v143
	v_exp_f32_e32 v160, v160
	v_exp_f32_e32 v161, v161
	v_exp_f32_e32 v142, v142
	v_exp_f32_e32 v143, v143
	v_add_f32_e32 v160, 1.0, v160
	v_add_f32_e32 v161, 1.0, v161
	v_add_f32_e32 v142, 1.0, v142
	v_add_f32_e32 v143, 1.0, v143
	v_rcp_f32_e32 v160, v160
	v_rcp_f32_e32 v161, v161
	v_rcp_f32_e32 v142, v142
	v_rcp_f32_e32 v143, v143
	v_pk_mul_f32 v[164:165], v[98:99], v[164:165]
	v_pk_mul_f32 v[142:143], v[166:167], v[142:143]
	v_pk_mul_f32 v[158:159], v[158:159], v[164:165]
	v_cvt_pk_bf16_f32 v165, v142, v143
	v_pk_mul_f32 v[158:159], v[158:159], v[160:161]
	s_nop 0
	v_cvt_pk_bf16_f32 v164, v158, v159
	ds_write_b128 v248, v[162:165] offset:49152
	s_waitcnt lgkmcnt(0)
	ds_read_b128 v[162:165], v249 offset:49152
	v_lshl_add_u64 v[140:141], v[140:141], 0, v[250:251]
	s_waitcnt lgkmcnt(0)
	global_store_dwordx4 v[140:141], v[162:165], off
	s_and_b64 vcc, exec, s[44:45]
	s_cbranch_vccz .LBB0_115

; __device__ __forceinline__ unsigned cvt_pk_bf16(float lo, float hi) { f32x2 v = {lo, hi}; bf16x2_t b = __builtin_convertvector(v, bf16x2_t); return __builtin_bit_cast(unsigned, b); }
; __device__ __forceinline__ float silu_mul(float g, float u) { return g * u * __builtin_amdgcn_rcpf(1.0f + __builtin_amdgcn_exp2f(-1.4426950408889634f * g)); }
;     __device__ __forceinline__ void operator()(const f32x4 (&acc)[2][2][4][2], const Unit& u, int wr, int wc, int fr, int fq) const {
;     ...
;                 if (mode == 2) {
;                     const f32x4 g0 = acc[ai][0][m][0] * r, g1 = acc[ai][0][m][1] * r, u0 = acc[ai][1][m][0] * r, u1 = acc[ai][1][m][1] * r;
;                     u32x4 w; w.x = cvt_pk_bf16(silu_mul(g0[0], u0[0]), silu_mul(g0[1], u0[1])); w.y = cvt_pk_bf16(silu_mul(g0[2], u0[2]), silu_mul(g0[3], u0[3]));
;                     w.z = cvt_pk_bf16(silu_mul(g1[0], u1[0]), silu_mul(g1[1], u1[1])); w.w = cvt_pk_bf16(silu_mul(g1[2], u1[2]), silu_mul(g1[3], u1[3]));
;                     *(u32x4*)rowp = w;
.LBB0_140:
	v_mov_b32_e32 v166, v164
	s_waitcnt lgkmcnt(0)
	v_mov_b32_e32 v167, v164
	v_pk_mul_f32 v[168:169], v[88:89], v[166:167]
	v_mul_f32_e32 v172, 0xbfb8aa3b, v162
	v_mul_f32_e32 v173, 0xbfb8aa3b, v163
	v_pk_mul_f32 v[168:169], v[160:161], v[168:169]
	v_mul_f32_e32 v160, 0xbfb8aa3b, v160
	v_mul_f32_e32 v161, 0xbfb8aa3b, v161
	v_exp_f32_e32 v172, v172
	v_exp_f32_e32 v173, v173
	v_exp_f32_e32 v160, v160
	v_exp_f32_e32 v161, v161
	v_add_f32_e32 v172, 1.0, v172
	v_add_f32_e32 v173, 1.0, v173
	v_add_f32_e32 v160, 1.0, v160
	v_add_f32_e32 v161, 1.0, v161
	v_rcp_f32_e32 v172, v172
	v_rcp_f32_e32 v173, v173
	v_rcp_f32_e32 v160, v160
	v_rcp_f32_e32 v161, v161
	v_pk_mul_f32 v[170:171], v[86:87], v[164:165]
	v_pk_mul_f32 v[166:167], v[84:85], v[166:167]
	v_pk_mul_f32 v[162:163], v[162:163], v[170:171]
	v_pk_mul_f32 v[160:161], v[168:169], v[160:161]
	v_pk_mul_f32 v[162:163], v[162:163], v[172:173]
	v_pk_mul_f32 v[166:167], v[142:143], v[166:167]
	v_cvt_pk_bf16_f32 v162, v162, v163
	v_cvt_pk_bf16_f32 v163, v160, v161
	v_mul_f32_e32 v160, 0xbfb8aa3b, v158
	v_mul_f32_e32 v161, 0xbfb8aa3b, v159
	v_mul_f32_e32 v142, 0xbfb8aa3b, v142
	v_mul_f32_e32 v143, 0xbfb8aa3b, v143
	v_exp_f32_e32 v160, v160
	v_exp_f32_e32 v161, v161
	v_exp_f32_e32 v142, v142
	v_exp_f32_e32 v143, v143
	v_add_f32_e32 v160, 1.0, v160
	v_add_f32_e32 v161, 1.0, v161
	v_add_f32_e32 v142, 1.0, v142
	v_add_f32_e32 v143, 1.0, v143
	v_rcp_f32_e32 v160, v160
	v_rcp_f32_e32 v161, v161
	v_rcp_f32_e32 v142, v142
	v_rcp_f32_e32 v143, v143
	v_pk_mul_f32 v[164:165], v[82:83], v[164:165]
	v_pk_mul_f32 v[142:143], v[166:167], v[142:143]
	v_pk_mul_f32 v[158:159], v[158:159], v[164:165]
	v_cvt_pk_bf16_f32 v165, v142, v143
	v_pk_mul_f32 v[158:159], v[158:159], v[160:161]
	s_nop 0
	v_cvt_pk_bf16_f32 v164, v158, v159
	ds_write_b128 v248, v[162:165] offset:49152
	s_waitcnt lgkmcnt(0)
	ds_read_b128 v[162:165], v249 offset:49152
	v_lshl_add_u64 v[140:141], v[140:141], 0, v[250:251]
	s_waitcnt lgkmcnt(0)
	global_store_dwordx4 v[140:141], v[162:165], off
	s_and_b64 vcc, exec, s[44:45]
	s_cbranch_vccz .LBB0_130

; __device__ __forceinline__ unsigned cvt_pk_bf16(float lo, float hi) { f32x2 v = {lo, hi}; bf16x2_t b = __builtin_convertvector(v, bf16x2_t); return __builtin_bit_cast(unsigned, b); }
; __device__ __forceinline__ float silu_mul(float g, float u) { return g * u * __builtin_amdgcn_rcpf(1.0f + __builtin_amdgcn_exp2f(-1.4426950408889634f * g)); }
;     __device__ __forceinline__ void operator()(const f32x4 (&acc)[2][2][4][2], const Unit& u, int wr, int wc, int fr, int fq) const {
;     ...
;                 if (mode == 2) {
;                     const f32x4 g0 = acc[ai][0][m][0] * r, g1 = acc[ai][0][m][1] * r, u0 = acc[ai][1][m][0] * r, u1 = acc[ai][1][m][1] * r;
;                     u32x4 w; w.x = cvt_pk_bf16(silu_mul(g0[0], u0[0]), silu_mul(g0[1], u0[1])); w.y = cvt_pk_bf16(silu_mul(g0[2], u0[2]), silu_mul(g0[3], u0[3]));
;                     w.z = cvt_pk_bf16(silu_mul(g1[0], u1[0]), silu_mul(g1[1], u1[1])); w.w = cvt_pk_bf16(silu_mul(g1[2], u1[2]), silu_mul(g1[3], u1[3]));
;                     *(u32x4*)rowp = w;
.LBB0_155:
	v_mov_b32_e32 v166, v164
	s_waitcnt lgkmcnt(0)
	v_mov_b32_e32 v167, v164
	v_pk_mul_f32 v[168:169], v[72:73], v[166:167]
	v_mul_f32_e32 v172, 0xbfb8aa3b, v162
	v_mul_f32_e32 v173, 0xbfb8aa3b, v163
	v_pk_mul_f32 v[168:169], v[160:161], v[168:169]
	v_mul_f32_e32 v160, 0xbfb8aa3b, v160
	v_mul_f32_e32 v161, 0xbfb8aa3b, v161
	v_exp_f32_e32 v172, v172
	v_exp_f32_e32 v173, v173
	v_exp_f32_e32 v160, v160
	v_exp_f32_e32 v161, v161
	v_add_f32_e32 v172, 1.0, v172
	v_add_f32_e32 v173, 1.0, v173
	v_add_f32_e32 v160, 1.0, v160
	v_add_f32_e32 v161, 1.0, v161
	v_rcp_f32_e32 v172, v172
	v_rcp_f32_e32 v173, v173
	v_rcp_f32_e32 v160, v160
	v_rcp_f32_e32 v161, v161
	v_pk_mul_f32 v[170:171], v[70:71], v[164:165]
	v_pk_mul_f32 v[166:167], v[68:69], v[166:167]
	v_pk_mul_f32 v[162:163], v[162:163], v[170:171]
	v_pk_mul_f32 v[160:161], v[168:169], v[160:161]
	v_pk_mul_f32 v[162:163], v[162:163], v[172:173]
	v_pk_mul_f32 v[166:167], v[142:143], v[166:167]
	v_cvt_pk_bf16_f32 v162, v162, v163
	v_cvt_pk_bf16_f32 v163, v160, v161
	v_mul_f32_e32 v160, 0xbfb8aa3b, v158
	v_mul_f32_e32 v161, 0xbfb8aa3b, v159
	v_mul_f32_e32 v142, 0xbfb8aa3b, v142
	v_mul_f32_e32 v143, 0xbfb8aa3b, v143
	v_exp_f32_e32 v160, v160
	v_exp_f32_e32 v161, v161
	v_exp_f32_e32 v142, v142
	v_exp_f32_e32 v143, v143
	v_add_f32_e32 v160, 1.0, v160
	v_add_f32_e32 v161, 1.0, v161
	v_add_f32_e32 v142, 1.0, v142
	v_add_f32_e32 v143, 1.0, v143
	v_rcp_f32_e32 v160, v160
	v_rcp_f32_e32 v161, v161
	v_rcp_f32_e32 v142, v142
	v_rcp_f32_e32 v143, v143
	v_pk_mul_f32 v[164:165], v[66:67], v[164:165]
	v_pk_mul_f32 v[142:143], v[166:167], v[142:143]
	v_pk_mul_f32 v[158:159], v[158:159], v[164:165]
	v_cvt_pk_bf16_f32 v165, v142, v143
	v_pk_mul_f32 v[158:159], v[158:159], v[160:161]
	s_nop 0
	v_cvt_pk_bf16_f32 v164, v158, v159
	ds_write_b128 v248, v[162:165] offset:49152
	s_waitcnt lgkmcnt(0)
	ds_read_b128 v[162:165], v249 offset:49152
	v_lshl_add_u64 v[140:141], v[140:141], 0, v[250:251]
	s_waitcnt lgkmcnt(0)
	global_store_dwordx4 v[140:141], v[162:165], off
	s_and_b64 vcc, exec, s[44:45]
	s_cbranch_vccz .LBB0_145

; __device__ __forceinline__ unsigned cvt_pk_bf16(float lo, float hi) { f32x2 v = {lo, hi}; bf16x2_t b = __builtin_convertvector(v, bf16x2_t); return __builtin_bit_cast(unsigned, b); }
; __device__ __forceinline__ float silu_mul(float g, float u) { return g * u * __builtin_amdgcn_rcpf(1.0f + __builtin_amdgcn_exp2f(-1.4426950408889634f * g)); }
;     __device__ __forceinline__ void operator()(const f32x4 (&acc)[2][2][4][2], const Unit& u, int wr, int wc, int fr, int fq) const {
;     ...
;                 if (mode == 2) {
;                     const f32x4 g0 = acc[ai][0][m][0] * r, g1 = acc[ai][0][m][1] * r, u0 = acc[ai][1][m][0] * r, u1 = acc[ai][1][m][1] * r;
;                     u32x4 w; w.x = cvt_pk_bf16(silu_mul(g0[0], u0[0]), silu_mul(g0[1], u0[1])); w.y = cvt_pk_bf16(silu_mul(g0[2], u0[2]), silu_mul(g0[3], u0[3]));
;                     w.z = cvt_pk_bf16(silu_mul(g1[0], u1[0]), silu_mul(g1[1], u1[1])); w.w = cvt_pk_bf16(silu_mul(g1[2], u1[2]), silu_mul(g1[3], u1[3]));
;                     *(u32x4*)rowp = w;
.LBB0_170:
	v_mov_b32_e32 v166, v164
	s_waitcnt lgkmcnt(0)
	v_mov_b32_e32 v167, v164
	v_pk_mul_f32 v[168:169], v[56:57], v[166:167]
	v_mul_f32_e32 v172, 0xbfb8aa3b, v162
	v_mul_f32_e32 v173, 0xbfb8aa3b, v163
	v_pk_mul_f32 v[168:169], v[160:161], v[168:169]
	v_mul_f32_e32 v160, 0xbfb8aa3b, v160
	v_mul_f32_e32 v161, 0xbfb8aa3b, v161
	v_exp_f32_e32 v172, v172
	v_exp_f32_e32 v173, v173
	v_exp_f32_e32 v160, v160
	v_exp_f32_e32 v161, v161
	v_add_f32_e32 v172, 1.0, v172
	v_add_f32_e32 v173, 1.0, v173
	v_add_f32_e32 v160, 1.0, v160
	v_add_f32_e32 v161, 1.0, v161
	v_rcp_f32_e32 v172, v172
	v_rcp_f32_e32 v173, v173
	v_rcp_f32_e32 v160, v160
	v_rcp_f32_e32 v161, v161
	v_pk_mul_f32 v[170:171], v[54:55], v[164:165]
	v_pk_mul_f32 v[166:167], v[52:53], v[166:167]
	v_pk_mul_f32 v[162:163], v[162:163], v[170:171]
	v_pk_mul_f32 v[160:161], v[168:169], v[160:161]
	v_pk_mul_f32 v[162:163], v[162:163], v[172:173]
	v_pk_mul_f32 v[166:167], v[142:143], v[166:167]
	v_cvt_pk_bf16_f32 v162, v162, v163
	v_cvt_pk_bf16_f32 v163, v160, v161
	v_mul_f32_e32 v160, 0xbfb8aa3b, v158
	v_mul_f32_e32 v161, 0xbfb8aa3b, v159
	v_mul_f32_e32 v142, 0xbfb8aa3b, v142
	v_mul_f32_e32 v143, 0xbfb8aa3b, v143
	v_exp_f32_e32 v160, v160
	v_exp_f32_e32 v161, v161
	v_exp_f32_e32 v142, v142
	v_exp_f32_e32 v143, v143
	v_add_f32_e32 v160, 1.0, v160
	v_add_f32_e32 v161, 1.0, v161
	v_add_f32_e32 v142, 1.0, v142
	v_add_f32_e32 v143, 1.0, v143
	v_rcp_f32_e32 v160, v160
	v_rcp_f32_e32 v161, v161
	v_rcp_f32_e32 v142, v142
	v_rcp_f32_e32 v143, v143
	v_pk_mul_f32 v[164:165], v[50:51], v[164:165]
	v_pk_mul_f32 v[142:143], v[166:167], v[142:143]
	v_pk_mul_f32 v[158:159], v[158:159], v[164:165]
	v_cvt_pk_bf16_f32 v165, v142, v143
	v_pk_mul_f32 v[158:159], v[158:159], v[160:161]
	s_nop 0
	v_cvt_pk_bf16_f32 v164, v158, v159
	ds_write_b128 v248, v[162:165] offset:49152
	s_waitcnt lgkmcnt(0)
	ds_read_b128 v[162:165], v249 offset:49152
	v_lshl_add_u64 v[140:141], v[140:141], 0, v[250:251]
	s_waitcnt lgkmcnt(0)
	global_store_dwordx4 v[140:141], v[162:165], off
	s_and_b64 vcc, exec, s[44:45]
	s_cbranch_vccz .LBB0_160

; __device__ __forceinline__ unsigned cvt_pk_bf16(float lo, float hi) { f32x2 v = {lo, hi}; bf16x2_t b = __builtin_convertvector(v, bf16x2_t); return __builtin_bit_cast(unsigned, b); }
; __device__ __forceinline__ float silu_mul(float g, float u) { return g * u * __builtin_amdgcn_rcpf(1.0f + __builtin_amdgcn_exp2f(-1.4426950408889634f * g)); }
;     __device__ __forceinline__ void operator()(const f32x4 (&acc)[2][2][4][2], const Unit& u, int wr, int wc, int fr, int fq) const {
;     ...
;                 if (mode == 2) {
;                     const f32x4 g0 = acc[ai][0][m][0] * r, g1 = acc[ai][0][m][1] * r, u0 = acc[ai][1][m][0] * r, u1 = acc[ai][1][m][1] * r;
;                     u32x4 w; w.x = cvt_pk_bf16(silu_mul(g0[0], u0[0]), silu_mul(g0[1], u0[1])); w.y = cvt_pk_bf16(silu_mul(g0[2], u0[2]), silu_mul(g0[3], u0[3]));
;                     w.z = cvt_pk_bf16(silu_mul(g1[0], u1[0]), silu_mul(g1[1], u1[1])); w.w = cvt_pk_bf16(silu_mul(g1[2], u1[2]), silu_mul(g1[3], u1[3]));
;                     *(u32x4*)rowp = w;
.LBB0_185:
	v_mov_b32_e32 v166, v164
	s_waitcnt lgkmcnt(0)
	v_mov_b32_e32 v167, v164
	v_pk_mul_f32 v[168:169], v[40:41], v[166:167]
	v_mul_f32_e32 v172, 0xbfb8aa3b, v162
	v_mul_f32_e32 v173, 0xbfb8aa3b, v163
	v_pk_mul_f32 v[168:169], v[160:161], v[168:169]
	v_mul_f32_e32 v160, 0xbfb8aa3b, v160
	v_mul_f32_e32 v161, 0xbfb8aa3b, v161
	v_exp_f32_e32 v172, v172
	v_exp_f32_e32 v173, v173
	v_exp_f32_e32 v160, v160
	v_exp_f32_e32 v161, v161
	v_add_f32_e32 v172, 1.0, v172
	v_add_f32_e32 v173, 1.0, v173
	v_add_f32_e32 v160, 1.0, v160
	v_add_f32_e32 v161, 1.0, v161
	v_rcp_f32_e32 v172, v172
	v_rcp_f32_e32 v173, v173
	v_rcp_f32_e32 v160, v160
	v_rcp_f32_e32 v161, v161
	v_pk_mul_f32 v[170:171], v[38:39], v[164:165]
	v_pk_mul_f32 v[166:167], v[36:37], v[166:167]
	v_pk_mul_f32 v[162:163], v[162:163], v[170:171]
	v_pk_mul_f32 v[160:161], v[168:169], v[160:161]
	v_pk_mul_f32 v[162:163], v[162:163], v[172:173]
	v_pk_mul_f32 v[166:167], v[142:143], v[166:167]
	v_cvt_pk_bf16_f32 v162, v162, v163
	v_cvt_pk_bf16_f32 v163, v160, v161
	v_mul_f32_e32 v160, 0xbfb8aa3b, v158
	v_mul_f32_e32 v161, 0xbfb8aa3b, v159
	v_mul_f32_e32 v142, 0xbfb8aa3b, v142
	v_mul_f32_e32 v143, 0xbfb8aa3b, v143
	v_exp_f32_e32 v160, v160
	v_exp_f32_e32 v161, v161
	v_exp_f32_e32 v142, v142
	v_exp_f32_e32 v143, v143
	v_add_f32_e32 v160, 1.0, v160
	v_add_f32_e32 v161, 1.0, v161
	v_add_f32_e32 v142, 1.0, v142
	v_add_f32_e32 v143, 1.0, v143
	v_rcp_f32_e32 v160, v160
	v_rcp_f32_e32 v161, v161
	v_rcp_f32_e32 v142, v142
	v_rcp_f32_e32 v143, v143
	v_pk_mul_f32 v[164:165], v[34:35], v[164:165]
	v_pk_mul_f32 v[142:143], v[166:167], v[142:143]
	v_pk_mul_f32 v[158:159], v[158:159], v[164:165]
	v_cvt_pk_bf16_f32 v165, v142, v143
	v_pk_mul_f32 v[158:159], v[158:159], v[160:161]
	s_nop 0
	v_cvt_pk_bf16_f32 v164, v158, v159
	ds_write_b128 v248, v[162:165] offset:49152
	s_waitcnt lgkmcnt(0)
	ds_read_b128 v[162:165], v249 offset:49152
	v_lshl_add_u64 v[140:141], v[140:141], 0, v[250:251]
	s_waitcnt lgkmcnt(0)
	global_store_dwordx4 v[140:141], v[162:165], off
	s_and_b64 vcc, exec, s[44:45]
	s_cbranch_vccz .LBB0_175

; __device__ __forceinline__ unsigned cvt_pk_bf16(float lo, float hi) { f32x2 v = {lo, hi}; bf16x2_t b = __builtin_convertvector(v, bf16x2_t); return __builtin_bit_cast(unsigned, b); }
; __device__ __forceinline__ float silu_mul(float g, float u) { return g * u * __builtin_amdgcn_rcpf(1.0f + __builtin_amdgcn_exp2f(-1.4426950408889634f * g)); }
;     __device__ __forceinline__ void operator()(const f32x4 (&acc)[2][2][4][2], const Unit& u, int wr, int wc, int fr, int fq) const {
;     ...
;                 if (mode == 2) {
;                     const f32x4 g0 = acc[ai][0][m][0] * r, g1 = acc[ai][0][m][1] * r, u0 = acc[ai][1][m][0] * r, u1 = acc[ai][1][m][1] * r;
;                     u32x4 w; w.x = cvt_pk_bf16(silu_mul(g0[0], u0[0]), silu_mul(g0[1], u0[1])); w.y = cvt_pk_bf16(silu_mul(g0[2], u0[2]), silu_mul(g0[3], u0[3]));
;                     w.z = cvt_pk_bf16(silu_mul(g1[0], u1[0]), silu_mul(g1[1], u1[1])); w.w = cvt_pk_bf16(silu_mul(g1[2], u1[2]), silu_mul(g1[3], u1[3]));
;                     *(u32x4*)rowp = w;
.LBB0_200:
	v_mov_b32_e32 v166, v164
	s_waitcnt lgkmcnt(0)
	v_mov_b32_e32 v167, v164
	v_pk_mul_f32 v[168:169], v[24:25], v[166:167]
	v_mul_f32_e32 v172, 0xbfb8aa3b, v162
	v_mul_f32_e32 v173, 0xbfb8aa3b, v163
	v_pk_mul_f32 v[168:169], v[160:161], v[168:169]
	v_mul_f32_e32 v160, 0xbfb8aa3b, v160
	v_mul_f32_e32 v161, 0xbfb8aa3b, v161
	v_exp_f32_e32 v172, v172
	v_exp_f32_e32 v173, v173
	v_exp_f32_e32 v160, v160
	v_exp_f32_e32 v161, v161
	v_add_f32_e32 v172, 1.0, v172
	v_add_f32_e32 v173, 1.0, v173
	v_add_f32_e32 v160, 1.0, v160
	v_add_f32_e32 v161, 1.0, v161
	v_rcp_f32_e32 v172, v172
	v_rcp_f32_e32 v173, v173
	v_rcp_f32_e32 v160, v160
	v_rcp_f32_e32 v161, v161
	v_pk_mul_f32 v[170:171], v[22:23], v[164:165]
	v_pk_mul_f32 v[166:167], v[20:21], v[166:167]
	v_pk_mul_f32 v[162:163], v[162:163], v[170:171]
	v_pk_mul_f32 v[160:161], v[168:169], v[160:161]
	v_pk_mul_f32 v[162:163], v[162:163], v[172:173]
	v_pk_mul_f32 v[166:167], v[142:143], v[166:167]
	v_cvt_pk_bf16_f32 v162, v162, v163
	v_cvt_pk_bf16_f32 v163, v160, v161
	v_mul_f32_e32 v160, 0xbfb8aa3b, v158
	v_mul_f32_e32 v161, 0xbfb8aa3b, v159
	v_mul_f32_e32 v142, 0xbfb8aa3b, v142
	v_mul_f32_e32 v143, 0xbfb8aa3b, v143
	v_exp_f32_e32 v160, v160
	v_exp_f32_e32 v161, v161
	v_exp_f32_e32 v142, v142
	v_exp_f32_e32 v143, v143
	v_add_f32_e32 v160, 1.0, v160
	v_add_f32_e32 v161, 1.0, v161
	v_add_f32_e32 v142, 1.0, v142
	v_add_f32_e32 v143, 1.0, v143
	v_rcp_f32_e32 v160, v160
	v_rcp_f32_e32 v161, v161
	v_rcp_f32_e32 v142, v142
	v_rcp_f32_e32 v143, v143
	v_pk_mul_f32 v[164:165], v[18:19], v[164:165]
	v_pk_mul_f32 v[142:143], v[166:167], v[142:143]
	v_pk_mul_f32 v[158:159], v[158:159], v[164:165]
	v_cvt_pk_bf16_f32 v165, v142, v143
	v_pk_mul_f32 v[158:159], v[158:159], v[160:161]
	s_nop 0
	v_cvt_pk_bf16_f32 v164, v158, v159
	ds_write_b128 v248, v[162:165] offset:49152
	s_waitcnt lgkmcnt(0)
	ds_read_b128 v[162:165], v249 offset:49152
	v_lshl_add_u64 v[140:141], v[140:141], 0, v[250:251]
	s_waitcnt lgkmcnt(0)
	global_store_dwordx4 v[140:141], v[162:165], off
	s_and_b64 vcc, exec, s[44:45]
	s_cbranch_vccz .LBB0_190

; __device__ __forceinline__ unsigned cvt_pk_bf16(float lo, float hi) { f32x2 v = {lo, hi}; bf16x2_t b = __builtin_convertvector(v, bf16x2_t); return __builtin_bit_cast(unsigned, b); }
; __device__ __forceinline__ float silu_mul(float g, float u) { return g * u * __builtin_amdgcn_rcpf(1.0f + __builtin_amdgcn_exp2f(-1.4426950408889634f * g)); }
;     __device__ __forceinline__ void operator()(const f32x4 (&acc)[2][2][4][2], const Unit& u, int wr, int wc, int fr, int fq) const {
;     ...
;                 if (mode == 2) {
;                     const f32x4 g0 = acc[ai][0][m][0] * r, g1 = acc[ai][0][m][1] * r, u0 = acc[ai][1][m][0] * r, u1 = acc[ai][1][m][1] * r;
;                     u32x4 w; w.x = cvt_pk_bf16(silu_mul(g0[0], u0[0]), silu_mul(g0[1], u0[1])); w.y = cvt_pk_bf16(silu_mul(g0[2], u0[2]), silu_mul(g0[3], u0[3]));
;                     w.z = cvt_pk_bf16(silu_mul(g1[0], u1[0]), silu_mul(g1[1], u1[1])); w.w = cvt_pk_bf16(silu_mul(g1[2], u1[2]), silu_mul(g1[3], u1[3]));
;                     *(u32x4*)rowp = w;
.LBB0_212:
	s_and_b64 vcc, exec, s[44:45]
	s_cbranch_vccz .LBB0_214
	v_mov_b32_e32 v162, v160
	s_waitcnt lgkmcnt(0)
	v_mov_b32_e32 v163, v160
	v_pk_mul_f32 v[164:165], v[8:9], v[162:163]
	v_mul_f32_e32 v168, 0xbfb8aa3b, v158
	v_mul_f32_e32 v169, 0xbfb8aa3b, v159
	v_pk_mul_f32 v[164:165], v[142:143], v[164:165]
	v_mul_f32_e32 v142, 0xbfb8aa3b, v142
	v_mul_f32_e32 v143, 0xbfb8aa3b, v143
	v_exp_f32_e32 v168, v168
	v_exp_f32_e32 v169, v169
	v_exp_f32_e32 v142, v142
	v_exp_f32_e32 v143, v143
	v_add_f32_e32 v168, 1.0, v168
	v_add_f32_e32 v169, 1.0, v169
	v_add_f32_e32 v142, 1.0, v142
	v_add_f32_e32 v143, 1.0, v143
	v_rcp_f32_e32 v168, v168
	v_rcp_f32_e32 v169, v169
	v_rcp_f32_e32 v142, v142
	v_rcp_f32_e32 v143, v143
	v_pk_mul_f32 v[166:167], v[6:7], v[160:161]
	v_pk_mul_f32 v[162:163], v[4:5], v[162:163]
	v_pk_mul_f32 v[158:159], v[158:159], v[166:167]
	v_pk_mul_f32 v[142:143], v[164:165], v[142:143]
	v_pk_mul_f32 v[158:159], v[158:159], v[168:169]
	v_pk_mul_f32 v[162:163], v[138:139], v[162:163]
	v_cvt_pk_bf16_f32 v158, v158, v159
	v_cvt_pk_bf16_f32 v159, v142, v143
	v_mul_f32_e32 v142, 0xbfb8aa3b, v140
	v_mul_f32_e32 v143, 0xbfb8aa3b, v141
	v_mul_f32_e32 v138, 0xbfb8aa3b, v138
	v_mul_f32_e32 v139, 0xbfb8aa3b, v139
	v_exp_f32_e32 v142, v142
	v_exp_f32_e32 v143, v143
	v_exp_f32_e32 v138, v138
	v_exp_f32_e32 v139, v139
	v_add_f32_e32 v142, 1.0, v142
	v_add_f32_e32 v143, 1.0, v143
	v_add_f32_e32 v138, 1.0, v138
	v_add_f32_e32 v139, 1.0, v139
	v_rcp_f32_e32 v142, v142
	v_rcp_f32_e32 v143, v143
	v_rcp_f32_e32 v138, v138
	v_rcp_f32_e32 v139, v139
	v_pk_mul_f32 v[160:161], v[2:3], v[160:161]
	v_pk_mul_f32 v[138:139], v[162:163], v[138:139]
	v_pk_mul_f32 v[140:141], v[140:141], v[160:161]
	v_cvt_pk_bf16_f32 v161, v138, v139
	v_pk_mul_f32 v[140:141], v[140:141], v[142:143]
	s_nop 0
	v_cvt_pk_bf16_f32 v160, v140, v141
	ds_write_b128 v248, v[158:161] offset:49152
	s_waitcnt lgkmcnt(0)
	ds_read_b128 v[158:161], v249 offset:49152
	v_lshl_add_u64 v[136:137], v[136:137], 0, v[250:251]
	s_waitcnt lgkmcnt(0)
	global_store_dwordx4 v[136:137], v[158:161], off
